# Hyena context tokens (layer 0): input taps batched; gate-row taps of the epilogue prefetched before the 256-step convolution loop
# speedup vs baseline: 1.0172x; 1.0008x over previous
; DI void hyena_unit(KP p, int l, int c, char* smem) {
;     ...
;         f32x4 uv;
;         if (o == 0) {
;           uv.x = sconv3(Zhc + (size_t)(0 * 1536 + c) * 256, t, 256, vw0, vw1, vw2, vb);
;           uv.y = sconv3(Zhc + (size_t)(1 * 1536 + c) * 256, t, 256, vw0, vw1, vw2, vb);
;           uv.z = sconv3(Zhc + (size_t)(2 * 1536 + c) * 256, t, 256, vw0, vw1, vw2, vb);
;           uv.w = sconv3(Zhc + (size_t)(3 * 1536 + c) * 256, t, 256, vw0, vw1, vw2, vb);
;         } else uv = mkf4(y1r[0], y1r[1], y1r[2], y1r[3]);
;         ((f32x4*)uu)[t] = uv;
;       }
;       __syncthreads();
;       {
;         f32x4 y = mkf4(0.f, 0.f, 0.f, 0.f);
; #pragma unroll 8
;         for (int s2 = 0; s2 < 256; ++s2) { const float kv = kk[255 + t - s2]; const f32x4 u4 = ((const f32x4*)uu)[s2]; y += kv * u4; }
;         const f32x4 ut = ((const f32x4*)uu)[t];
;         const float yy[4] = {y.x, y.y, y.z, y.w}, us[4] = {ut.x, ut.y, ut.z, ut.w};
; #pragma unroll
;         for (int b = 0; b < 4; ++b) {
;           const float xg = sconv3(Zhc + (size_t)(b * 1536 + gcol) * 256, t, 256, gw0, gw1, gw2, gb);
;           const float ov = xg * yy[b];
.LBB0_1033:
	s_or_b64 exec, exec, s[22:23]
	v_mov_b64_e32 v[8:9], v[4:5]
	s_andn2_b64 vcc, exec, s[16:17]
	v_mov_b64_e32 v[6:7], v[2:3]
	s_cbranch_vccnz .LBB0_1051
	global_load_ushort v6, v[16:17], off offset:-2
	global_load_ushort v53, v[18:19], off
	global_load_ushort v7, v[18:19], off offset:2
	global_load_ushort v8, v[20:21], off offset:-2
	global_load_ushort v54, v[22:23], off
	global_load_ushort v9, v[22:23], off offset:2
	global_load_ushort v10, v[24:25], off offset:-2
	global_load_ushort v55, v[26:27], off
	global_load_ushort v11, v[26:27], off offset:2
	global_load_ushort v12, v[28:29], off offset:-2
	global_load_ushort v56, v[30:31], off
	global_load_ushort v13, v[30:31], off offset:2
	s_waitcnt vmcnt(0)
	v_lshlrev_b32_e32 v6, 16, v6
	v_lshlrev_b32_e32 v7, 16, v7
	v_cndmask_b32_e64 v6, 0, v6, s[12:13]
	v_cndmask_b32_e64 v7, 0, v7, s[14:15]
	v_lshlrev_b32_e32 v8, 16, v8
	v_lshlrev_b32_e32 v9, 16, v9
	v_cndmask_b32_e64 v8, 0, v8, s[12:13]
	v_cndmask_b32_e64 v9, 0, v9, s[14:15]
	v_lshlrev_b32_e32 v10, 16, v10
	v_lshlrev_b32_e32 v11, 16, v11
	v_cndmask_b32_e64 v10, 0, v10, s[12:13]
	v_cndmask_b32_e64 v11, 0, v11, s[14:15]
	v_lshlrev_b32_e32 v12, 16, v12
	v_lshlrev_b32_e32 v13, 16, v13
	v_cndmask_b32_e64 v12, 0, v12, s[12:13]
	v_cndmask_b32_e64 v13, 0, v13, s[14:15]
	s_waitcnt vmcnt(3)
	v_lshlrev_b32_e32 v53, 16, v53
	v_pk_mul_f32 v[6:7], v[40:41], v[6:7]
	v_pk_mul_f32 v[8:9], v[40:41], v[8:9]
	v_fma_f32 v6, v51, v53, v6
	v_add_f32_e32 v6, v6, v7
	s_waitcnt vmcnt(2)
	v_lshlrev_b32_e32 v7, 16, v54
	v_fma_f32 v7, v51, v7, v8
	v_add_f32_e32 v7, v7, v9
	s_waitcnt vmcnt(1)
	v_lshlrev_b32_e32 v53, 16, v55
	v_pk_mul_f32 v[8:9], v[40:41], v[10:11]
	v_pk_mul_f32 v[10:11], v[40:41], v[12:13]
	v_fma_f32 v8, v51, v53, v8
	v_add_f32_e32 v8, v8, v9
	s_waitcnt vmcnt(0)
	v_lshlrev_b32_e32 v9, 16, v56
	v_fma_f32 v9, v51, v9, v10
	v_add_f32_e32 v9, v9, v11
	v_add_f32_e32 v6, v52, v6
	v_add_f32_e32 v7, v52, v7
	v_add_f32_e32 v8, v52, v8
	v_add_f32_e32 v9, v52, v9
.LBB0_1051:
	ds_write_b128 v43, v[6:9] offset:2048
	v_mov_b32_e32 v8, 0
	s_xor_b64 s[22:23], s[16:17], -1
	s_movk_i32 s16, 0x800
	s_movk_i32 s17, 0x3e0
	v_mov_b32_e32 v9, v8
	v_mov_b32_e32 v6, v8
	v_mov_b32_e32 v7, v8
	s_waitcnt lgkmcnt(0)
	s_barrier
	s_add_i32 s98, s7, s86
	s_ashr_i32 s99, s98, 31
	s_lshl_b64 s[98:99], s[98:99], 9
	s_add_u32 s98, s29, s98
	s_addc_u32 s99, s34, s99
	v_lshl_add_u64 v[116:117], v[66:67], 1, s[98:99]
	s_mov_b64 s[98:99], 0xc0000
	v_lshl_add_u64 v[118:119], v[116:117], 0, s[98:99]
	v_lshl_add_u64 v[120:121], v[118:119], 0, s[98:99]
	v_lshl_add_u64 v[122:123], v[120:121], 0, s[98:99]
	global_load_ushort v104, v[116:117], off offset:-2
	global_load_ushort v105, v[116:117], off
	global_load_ushort v106, v[116:117], off offset:2
	global_load_ushort v107, v[118:119], off offset:-2
	global_load_ushort v108, v[118:119], off
	global_load_ushort v109, v[118:119], off offset:2
	global_load_ushort v110, v[120:121], off offset:-2
	global_load_ushort v111, v[120:121], off
	global_load_ushort v112, v[120:121], off offset:2
	global_load_ushort v113, v[122:123], off offset:-2
	global_load_ushort v114, v[122:123], off
	global_load_ushort v115, v[122:123], off offset:2
.LBB0_1052:
	v_add_u32_e32 v51, s17, v44
	ds_read2_b32 v[40:41], v51 offset0:6 offset1:7
	v_mov_b32_e32 v64, s16
	ds_read_b128 v[10:13], v64
	ds_read_b128 v[52:55], v64 offset:16
	ds_read_b128 v[56:59], v64 offset:32
	ds_read_b128 v[60:63], v64 offset:48
	s_addk_i32 s16, 0x80
	s_sub_i32 s17, s17, 32
	s_waitcnt lgkmcnt(3)
	v_pk_fma_f32 v[8:9], v[10:11], v[40:41], v[8:9] op_sel:[0,1,0]
	ds_read2_b32 v[10:11], v51 offset0:4 offset1:5
	v_pk_fma_f32 v[6:7], v[12:13], v[40:41], v[6:7] op_sel:[0,1,0]
	s_waitcnt lgkmcnt(3)
	v_pk_fma_f32 v[8:9], v[52:53], v[40:41], v[8:9] op_sel_hi:[1,0,1]
	v_pk_fma_f32 v[6:7], v[54:55], v[40:41], v[6:7] op_sel_hi:[1,0,1]
	s_cmpk_eq_i32 s17, 0xffe0
	s_waitcnt lgkmcnt(0)
	v_pk_fma_f32 v[6:7], v[58:59], v[10:11], v[6:7] op_sel:[0,1,0]
	v_pk_fma_f32 v[8:9], v[56:57], v[10:11], v[8:9] op_sel:[0,1,0]
	v_pk_fma_f32 v[12:13], v[62:63], v[10:11], v[6:7] op_sel_hi:[1,0,1]
	v_pk_fma_f32 v[10:11], v[60:61], v[10:11], v[8:9] op_sel_hi:[1,0,1]
	ds_read2_b32 v[40:41], v51 offset0:2 offset1:3
	ds_read_b128 v[6:9], v64 offset:64
	s_waitcnt lgkmcnt(0)
	v_pk_fma_f32 v[12:13], v[8:9], v[40:41], v[12:13] op_sel:[0,1,0]
	v_pk_fma_f32 v[10:11], v[6:7], v[40:41], v[10:11] op_sel:[0,1,0]
	ds_read_b128 v[6:9], v64 offset:80
	s_waitcnt lgkmcnt(0)
	v_pk_fma_f32 v[12:13], v[8:9], v[40:41], v[12:13] op_sel_hi:[1,0,1]
	v_pk_fma_f32 v[10:11], v[6:7], v[40:41], v[10:11] op_sel_hi:[1,0,1]
	ds_read2_b32 v[40:41], v51 offset1:1
	ds_read_b128 v[6:9], v64 offset:96
	s_waitcnt lgkmcnt(0)
	v_pk_fma_f32 v[12:13], v[8:9], v[40:41], v[12:13] op_sel:[0,1,0]
	v_pk_fma_f32 v[52:53], v[6:7], v[40:41], v[10:11] op_sel:[0,1,0]
	ds_read_b128 v[8:11], v64 offset:112
	s_waitcnt lgkmcnt(0)
	v_pk_fma_f32 v[6:7], v[10:11], v[40:41], v[12:13] op_sel_hi:[1,0,1]
	v_pk_fma_f32 v[8:9], v[8:9], v[40:41], v[52:53] op_sel_hi:[1,0,1]
	s_cbranch_scc0 .LBB0_1052
	s_add_i32 s16, s7, s86
	s_ashr_i32 s17, s16, 31
	s_lshl_b64 s[24:25], s[16:17], 9
	s_add_u32 s16, s29, s24
	s_addc_u32 s17, s34, s25
	s_waitcnt vmcnt(0)
	v_lshlrev_b32_e32 v13, 16, v104
	v_lshlrev_b32_e32 v12, 16, v106
	v_mov_b32_e32 v40, v105
	v_cndmask_b32_e64 v13, 0, v13, s[12:13]
	v_cndmask_b32_e64 v12, 0, v12, s[14:15]
	s_waitcnt vmcnt(0)
	v_lshlrev_b32_e32 v10, 16, v40
	v_mul_f32_e32 v10, v49, v10
	v_fmac_f32_e32 v10, v47, v13
	v_fmac_f32_e32 v10, v48, v12
	v_add_f32_e32 v10, v50, v10
	v_mul_f32_e32 v8, v8, v10
	s_and_b64 vcc, exec, s[22:23]
	s_cbranch_vccz .LBB0_1061
	v_cvt_pk_bf16_f32 v8, v8, s0
	global_store_short v[32:33], v8, off
	s_branch .LBB0_1062

; DI void hyena_unit(KP p, int l, int c, char* smem) {
;     ...
;         for (int b = 0; b < 4; ++b) {
;           const float xg = sconv3(Zhc + (size_t)(b * 1536 + gcol) * 256, t, 256, gw0, gw1, gw2, gb);
;           const float ov = xg * yy[b];
;           if (o == 0) y1r[b] = ov;
;           else yct[(size_t)NB * 512 * 4096 + (size_t)(b * 512 + c) * 256 + t] = f2bf(ov);
.LBB0_1062:
	s_add_u32 s7, s29, s24
	s_addc_u32 s17, s34, s25
	s_add_u32 s16, s7, 0xc0000
	s_addc_u32 s17, s17, 0
	v_lshlrev_b32_e32 v12, 16, v107
	v_lshlrev_b32_e32 v8, 16, v109
	v_mov_b32_e32 v13, v108
	v_cndmask_b32_e64 v12, 0, v12, s[12:13]
	v_cndmask_b32_e64 v8, 0, v8, s[14:15]
	s_waitcnt vmcnt(0)
	v_lshlrev_b32_e32 v10, 16, v13
	v_mul_f32_e32 v10, v49, v10
	v_fmac_f32_e32 v10, v47, v12
	v_fmac_f32_e32 v10, v48, v8
	v_add_f32_e32 v8, v50, v10
	v_cndmask_b32_e64 v10, 0, 1, s[22:23]
	v_cmp_ne_u32_e64 s[16:17], 1, v10
	s_andn2_b64 vcc, exec, s[22:23]
	v_mul_f32_e32 v8, v9, v8
	s_cbranch_vccnz .LBB0_1068
	v_cvt_pk_bf16_f32 v8, v8, s0
	s_mov_b64 s[22:23], 0
	global_store_short v[34:35], v8, off
	s_branch .LBB0_1069

; DI void hyena_unit(KP p, int l, int c, char* smem) {
;     ...
;         for (int b = 0; b < 4; ++b) {
;           const float xg = sconv3(Zhc + (size_t)(b * 1536 + gcol) * 256, t, 256, gw0, gw1, gw2, gb);
;           const float ov = xg * yy[b];
;           if (o == 0) y1r[b] = ov;
;           else yct[(size_t)NB * 512 * 4096 + (size_t)(b * 512 + c) * 256 + t] = f2bf(ov);
.LBB0_1069:
	s_andn2_b64 vcc, exec, s[22:23]
	s_add_u32 s7, s29, s24
	s_addc_u32 s23, s34, s25
	s_add_u32 s22, s7, 0x180000
	s_addc_u32 s23, s23, 0
	v_lshlrev_b32_e32 v11, 16, v110
	v_lshlrev_b32_e32 v10, 16, v112
	v_mov_b32_e32 v12, v111
	v_cndmask_b32_e64 v11, 0, v11, s[12:13]
	v_cndmask_b32_e64 v10, 0, v10, s[14:15]
	s_waitcnt vmcnt(0)
	v_lshlrev_b32_e32 v8, 16, v12
	v_mul_f32_e32 v8, v49, v8
	v_fmac_f32_e32 v8, v47, v11
	v_fmac_f32_e32 v8, v48, v10
	v_add_f32_e32 v8, v50, v8
	s_and_b64 vcc, exec, s[16:17]
	v_mul_f32_e32 v6, v6, v8
	s_cbranch_vccnz .LBB0_1075
	v_cvt_pk_bf16_f32 v6, v6, s0
	s_mov_b64 s[22:23], 0
	global_store_short v[36:37], v6, off
	s_branch .LBB0_1076

; DI void hyena_unit(KP p, int l, int c, char* smem) {
;     ...
;         for (int b = 0; b < 4; ++b) {
;           const float xg = sconv3(Zhc + (size_t)(b * 1536 + gcol) * 256, t, 256, gw0, gw1, gw2, gb);
;           const float ov = xg * yy[b];
;           if (o == 0) y1r[b] = ov;
;           else yct[(size_t)NB * 512 * 4096 + (size_t)(b * 512 + c) * 256 + t] = f2bf(ov);
.LBB0_1076:
	s_andn2_b64 vcc, exec, s[22:23]
	s_add_u32 s7, s29, s24
	s_addc_u32 s23, s34, s25
	s_add_u32 s22, s7, 0x240000
	s_addc_u32 s23, s23, 0
	v_lshlrev_b32_e32 v10, 16, v113
	v_lshlrev_b32_e32 v6, 16, v115
	v_mov_b32_e32 v11, v114
	v_cndmask_b32_e64 v10, 0, v10, s[12:13]
	v_cndmask_b32_e64 v6, 0, v6, s[14:15]
	s_waitcnt vmcnt(0)
	v_lshlrev_b32_e32 v8, 16, v11
	v_mul_f32_e32 v8, v49, v8
	v_fmac_f32_e32 v8, v47, v10
	v_fmac_f32_e32 v8, v48, v6
	v_add_f32_e32 v6, v50, v8
	s_and_b64 vcc, exec, s[16:17]
	v_mul_f32_e32 v6, v7, v6
	s_cbranch_vccz .LBB0_1027
	v_mov_b32_e32 v5, v6
	s_mov_b64 s[22:23], -1
	s_branch .LBB0_1028
